# MoBA packed loop last-chunk copy: same fall-through layout (single-tile init, both rescales and the single-tile tail out of line)
# baseline (speedup 1.0000x reference)
.LBB0_1932:
	s_waitcnt vmcnt(7)
	ds_write_b128 v243, v[128:131]
	s_waitcnt vmcnt(6)
	ds_write_b128 v244, v[132:135] offset:4608
	s_waitcnt vmcnt(5)
	ds_write_b128 v243, v[136:139] offset:1152
	s_waitcnt vmcnt(4)
	ds_write_b128 v244, v[140:143] offset:5120
	s_waitcnt vmcnt(3)
	ds_write_b128 v243, v[144:147] offset:2304
	s_waitcnt vmcnt(2)
	ds_write_b128 v244, v[148:151] offset:5632
	s_waitcnt vmcnt(1)
	ds_write_b128 v243, v[152:155] offset:3456
	s_waitcnt vmcnt(0)
	ds_write_b128 v244, v[156:159] offset:6144
	s_waitcnt lgkmcnt(0)
	ds_read_b128 v[6:9], v242
	ds_read_b128 v[2:5], v242 offset:32
	ds_read_b128 v[10:13], v242 offset:8704
	v_xor_b32_e32 v112, 0x80000000, v1
	v_mov_b32_e32 v113, v112
	v_mov_b32_e32 v114, v112
	v_mov_b32_e32 v115, v112
	v_mov_b32_e32 v116, v112
	v_mov_b32_e32 v117, v112
	v_mov_b32_e32 v118, v112
	v_mov_b32_e32 v119, v112
	v_mov_b32_e32 v120, v112
	v_mov_b32_e32 v121, v112
	v_mov_b32_e32 v122, v112
	v_mov_b32_e32 v123, v112
	v_mov_b32_e32 v124, v112
	v_mov_b32_e32 v125, v112
	v_mov_b32_e32 v126, v112
	v_mov_b32_e32 v127, v112
	ds_read_b128 v[96:99], v242 offset:8736
	s_and_b64 vcc, exec, s[22:23]
	s_waitcnt lgkmcnt(1)
	v_mfma_f32_32x32x16_bf16 v[112:127], v[6:9], v[10:13], v[112:127]
	s_waitcnt lgkmcnt(0)
	v_mfma_f32_32x32x16_bf16 v[112:127], v[2:5], v[96:99], v[112:127]
	ds_read_b128 v[10:13], v242 offset:64
	ds_read_b128 v[96:99], v242 offset:8768
	ds_read_b128 v[128:131], v242 offset:96
	ds_read_b128 v[100:103], v242 offset:8800
	s_waitcnt lgkmcnt(2)
	v_mfma_f32_32x32x16_bf16 v[112:127], v[10:13], v[96:99], v[112:127]
	v_xor_b32_e32 v96, 0x80000000, v15
	v_mov_b32_e32 v97, v96
	v_mov_b32_e32 v98, v96
	v_mov_b32_e32 v99, v96
	v_mov_b32_e32 v104, v96
	v_mov_b32_e32 v105, v96
	v_mov_b32_e32 v106, v96
	s_waitcnt lgkmcnt(0)
	v_mfma_f32_32x32x16_bf16 v[112:127], v[128:131], v[100:103], v[112:127]
	v_mov_b32_e32 v100, v96
	v_mov_b32_e32 v101, v96
	v_mov_b32_e32 v102, v96
	v_mov_b32_e32 v103, v96
	v_mov_b32_e32 v107, v96
	v_mov_b32_e32 v108, v96
	s_cbranch_vccnz .LBB0_1934
	ds_read_b128 v[132:135], v242 offset:13312
	ds_read_b128 v[136:139], v242 offset:13344
	v_mov_b32_e32 v109, v96
	v_mov_b32_e32 v110, v96
	v_mov_b32_e32 v111, v96
	s_waitcnt lgkmcnt(1)
	s_nop 0
	v_mfma_f32_32x32x16_bf16 v[96:111], v[6:9], v[132:135], v[96:111]
	s_waitcnt lgkmcnt(0)
	v_mfma_f32_32x32x16_bf16 v[96:111], v[2:5], v[136:139], v[96:111]
	ds_read_b128 v[2:5], v242 offset:13376
	ds_read_b128 v[6:9], v242 offset:13408
	s_waitcnt lgkmcnt(1)
	v_mfma_f32_32x32x16_bf16 v[96:111], v[10:13], v[2:5], v[96:111]
	s_waitcnt lgkmcnt(0)
	v_mfma_f32_32x32x16_bf16 v[96:111], v[128:131], v[6:9], v[96:111]
.LBB0_1935:
	v_max_f32_e32 v2, v112, v113
	v_max3_f32 v2, v2, v114, v115
	v_max3_f32 v2, v2, v116, v117
	v_max3_f32 v2, v2, v118, v119
	v_max3_f32 v2, v2, v120, v121
	v_max3_f32 v2, v2, v122, v123
	v_max3_f32 v2, v2, v124, v125
	v_max3_f32 v2, v2, v126, v127
	v_mov_b32_e32 v3, v2
	s_nop 1
	v_permlane32_swap_b32_e32 v2, v3
	v_max_f32_e32 v2, v2, v3
	v_cmp_lt_f32_e32 vcc, s88, v2
	s_cbranch_vccnz .Lmt_rescA
.LBB0_1937:
	v_exp_f32_e32 v128, v112
	v_exp_f32_e32 v129, v113
	v_exp_f32_e32 v130, v114
	v_exp_f32_e32 v131, v115
	v_exp_f32_e32 v116, v116
	v_exp_f32_e32 v117, v117
	v_exp_f32_e32 v118, v118
	v_exp_f32_e32 v119, v119
	v_exp_f32_e32 v120, v120
	v_exp_f32_e32 v121, v121
	v_exp_f32_e32 v122, v122
	v_exp_f32_e32 v123, v123
	v_exp_f32_e32 v124, v124
	v_exp_f32_e32 v125, v125
	v_exp_f32_e32 v126, v126
	v_exp_f32_e32 v127, v127
	v_cvt_pk_bf16_f32 v132, v128, v129
	v_cvt_pk_bf16_f32 v133, v130, v131
	v_cvt_pk_bf16_f32 v134, v116, v117
	v_cvt_pk_bf16_f32 v135, v118, v119
	v_cvt_pk_bf16_f32 v136, v120, v121
	v_cvt_pk_bf16_f32 v137, v122, v123
	v_cvt_pk_bf16_f32 v138, v124, v125
	v_cvt_pk_bf16_f32 v139, v126, v127
	ds_read_b64_tr_b16 v[10:11], v241 offset:4608
	ds_read_b64_tr_b16 v[12:13], v241 offset:5120
	ds_read_b64_tr_b16 v[2:3], v241 offset:5632
	ds_read_b64_tr_b16 v[4:5], v241 offset:6144
	ds_read_b64_tr_b16 v[112:113], v241 offset:6656
	ds_read_b64_tr_b16 v[114:115], v241 offset:7168
	ds_read_b64_tr_b16 v[6:7], v241 offset:7680
	ds_read_b64_tr_b16 v[8:9], v241 offset:8192
	s_waitcnt lgkmcnt(6)
	v_mfma_f32_32x32x16_bf16 v[48:63], v[10:13], v[132:135], v[48:63]
	s_waitcnt lgkmcnt(0)
	s_and_b64 vcc, exec, s[22:23]
	s_waitcnt lgkmcnt(2)
	v_mfma_f32_32x32x16_bf16 v[64:79], v[112:115], v[132:135], v[64:79]
	v_mfma_f32_32x32x16_bf16 v[48:63], v[2:5], v[136:139], v[48:63]
	s_waitcnt lgkmcnt(0)
	v_mfma_f32_32x32x16_bf16 v[64:79], v[6:9], v[136:139], v[64:79]
	s_cbranch_vccnz .LBB0_1941
	v_max_f32_e32 v132, v96, v97
	v_max3_f32 v132, v132, v98, v99
	v_max3_f32 v132, v132, v100, v101
	v_max3_f32 v132, v132, v102, v103
	v_max3_f32 v132, v132, v104, v105
	v_max3_f32 v132, v132, v106, v107
	v_max3_f32 v132, v132, v108, v109
	v_max3_f32 v132, v132, v110, v111
	v_mov_b32_e32 v133, v132
	s_nop 1
	v_permlane32_swap_b32_e32 v132, v133
	v_max_f32_e32 v132, v132, v133
	v_cmp_lt_f32_e32 vcc, s88, v132
	s_cbranch_vccnz .Lmt_rescB
.LBB0_1940:
	v_exp_f32_e32 v133, v96
	v_exp_f32_e32 v132, v97
	v_exp_f32_e32 v135, v98
	v_exp_f32_e32 v134, v99
	v_exp_f32_e32 v137, v100
	v_exp_f32_e32 v136, v101
	v_exp_f32_e32 v101, v102
	v_exp_f32_e32 v100, v103
	v_cvt_pk_bf16_f32 v96, v133, v132
	v_cvt_pk_bf16_f32 v97, v135, v134
	v_cvt_pk_bf16_f32 v98, v137, v136
	v_cvt_pk_bf16_f32 v99, v101, v100
	v_exp_f32_e32 v103, v104
	v_mfma_f32_32x32x16_bf16 v[80:95], v[10:13], v[96:99], v[80:95]
	v_exp_f32_e32 v102, v105
	v_pk_add_f32 v[10:11], v[132:133], 0 op_sel_hi:[1,0]
	v_exp_f32_e32 v105, v106
	v_exp_f32_e32 v104, v107
	v_pk_add_f32 v[10:11], v[134:135], v[10:11]
	v_exp_f32_e32 v107, v108
	v_exp_f32_e32 v106, v109
	v_mfma_f32_32x32x16_bf16 v[32:47], v[112:115], v[96:99], v[32:47]
	v_exp_f32_e32 v109, v110
	v_exp_f32_e32 v108, v111
	v_pk_add_f32 v[96:97], v[136:137], v[10:11]
	v_cvt_pk_bf16_f32 v10, v103, v102
	v_cvt_pk_bf16_f32 v11, v105, v104
	v_cvt_pk_bf16_f32 v12, v107, v106
	v_cvt_pk_bf16_f32 v13, v109, v108
	s_nop 0
	v_mfma_f32_32x32x16_bf16 v[80:95], v[2:5], v[10:13], v[80:95]
	v_add_f32_e64 v2, v100, v96
	v_add_f32_e64 v3, v101, v97
	v_add_f32_e64 v2, v102, v2
	v_add_f32_e64 v3, v103, v3
	v_add_f32_e64 v2, v104, v2
	v_add_f32_e64 v3, v105, v3
	v_pk_add_f32 v[2:3], v[106:107], v[2:3]
	v_mfma_f32_32x32x16_bf16 v[32:47], v[6:9], v[10:13], v[32:47]
	v_add_f32_e64 v2, v108, v2
	v_add_f32_e64 v3, v109, v3
	v_add_f32_e32 v2, v2, v3
	v_add_f32_e32 v14, v14, v2
.LBB0_1942:
	v_add_f32_e32 v2, 0, v128
	v_add_f32_e32 v3, 0, v129
	v_add_f32_e32 v2, v130, v2
	v_add_f32_e32 v3, v131, v3
	v_add_f32_e32 v2, v116, v2
	v_add_f32_e32 v3, v117, v3
	v_add_f32_e32 v2, v118, v2
	v_add_f32_e32 v3, v119, v3
	v_add_f32_e32 v2, v120, v2
	v_add_f32_e32 v3, v121, v3
	v_add_f32_e32 v2, v122, v2
	v_add_f32_e32 v3, v123, v3
	v_add_f32_e32 v2, v124, v2
	v_add_f32_e32 v3, v125, v3
	v_add_f32_e32 v2, v126, v2
	v_add_f32_e32 v3, v127, v3
	v_add_f32_e32 v2, v3, v2
	ds_read_b32 v6, v166
	ds_read_b32 v3, v181
	v_add_f32_e32 v4, v240, v2
	v_mov_b32_e32 v5, v4
	v_mov_b32_e32 v2, v14
	s_nop 0
	v_permlane32_swap_b32_e32 v4, v5
	v_permlane32_swap_b32_e32 v14, v2
	s_and_saveexec_b64 s[20:21], s[18:19]
	s_cbranch_execz .LBB0_1945
	s_waitcnt lgkmcnt(1)
	v_lshrrev_b32_e32 v7, 8, v6
	v_and_b32_e32 v6, 0xff, v6
	v_mad_u32_u24 v166, v6, 3, v7
	v_lshlrev_b64 v[6:7], 8, v[166:167]
	v_lshl_add_u64 v[6:7], v[172:173], 0, v[6:7]
	global_store_dwordx4 v[6:7], v[48:51], off
	global_store_dwordx4 v[6:7], v[64:67], off offset:128
	global_store_dwordx4 v[6:7], v[52:55], off offset:32
	global_store_dwordx4 v[6:7], v[68:71], off offset:160
	global_store_dwordx4 v[6:7], v[56:59], off offset:64
	global_store_dwordx4 v[6:7], v[72:75], off offset:192
	global_store_dwordx4 v[6:7], v[60:63], off offset:96
	global_store_dwordx4 v[6:7], v[76:79], off offset:224
	s_and_b64 exec, exec, s[2:3]
	s_cbranch_execz .LBB0_1945
	v_add_f32_e32 v4, v4, v5
	v_lshlrev_b32_e32 v5, 2, v166
	global_store_dword v5, v4, s[46:47]
	global_store_dword v5, v1, s[48:49]
.LBB0_1945:
	s_or_b64 exec, exec, s[20:21]
	s_and_saveexec_b64 s[18:19], s[24:25]
	s_cbranch_execz .LBB0_1913
	s_waitcnt lgkmcnt(0)
	v_and_b32_e32 v1, 0xff, v3
	v_lshrrev_b32_e32 v3, 8, v3
	v_mad_u32_u24 v166, v1, 3, v3
	v_lshlrev_b64 v[4:5], 8, v[166:167]
	v_lshl_add_u64 v[4:5], v[172:173], 0, v[4:5]
	global_store_dwordx4 v[4:5], v[80:83], off
	global_store_dwordx4 v[4:5], v[32:35], off offset:128
	global_store_dwordx4 v[4:5], v[84:87], off offset:32
	global_store_dwordx4 v[4:5], v[36:39], off offset:160
	global_store_dwordx4 v[4:5], v[88:91], off offset:64
	global_store_dwordx4 v[4:5], v[40:43], off offset:192
	global_store_dwordx4 v[4:5], v[92:95], off offset:96
	global_store_dwordx4 v[4:5], v[44:47], off offset:224
	s_and_b64 exec, exec, s[2:3]
	s_cbranch_execz .LBB0_1913
	v_add_f32_e32 v1, v14, v2
	v_lshlrev_b32_e32 v2, 2, v166
	global_store_dword v2, v1, s[46:47]
	global_store_dword v2, v15, s[48:49]
	s_branch .LBB0_1913
.LBB0_1934:
	v_mov_b32_e32 v109, v96
	v_mov_b32_e32 v110, v96
	v_mov_b32_e32 v111, v96
	s_branch .LBB0_1935

.Lmt_rescB:
	v_max_f32_e32 v132, v132, v132
	v_max_f32_e32 v132, 0, v132
	v_exp_f32_e64 v134, -v132
	v_add_f32_e32 v15, v15, v132
	v_pk_add_f32 v[96:97], v[96:97], v[132:133] op_sel_hi:[1,0] neg_lo:[0,1] neg_hi:[0,1]
	v_pk_add_f32 v[98:99], v[98:99], v[132:133] op_sel_hi:[1,0] neg_lo:[0,1] neg_hi:[0,1]
	v_pk_add_f32 v[100:101], v[100:101], v[132:133] op_sel_hi:[1,0] neg_lo:[0,1] neg_hi:[0,1]
	v_pk_add_f32 v[102:103], v[102:103], v[132:133] op_sel_hi:[1,0] neg_lo:[0,1] neg_hi:[0,1]
	v_pk_add_f32 v[104:105], v[104:105], v[132:133] op_sel_hi:[1,0] neg_lo:[0,1] neg_hi:[0,1]
	v_pk_add_f32 v[106:107], v[106:107], v[132:133] op_sel_hi:[1,0] neg_lo:[0,1] neg_hi:[0,1]
	v_pk_add_f32 v[108:109], v[108:109], v[132:133] op_sel_hi:[1,0] neg_lo:[0,1] neg_hi:[0,1]
	v_pk_add_f32 v[110:111], v[110:111], v[132:133] op_sel_hi:[1,0] neg_lo:[0,1] neg_hi:[0,1]
	v_mul_f32_e32 v14, v14, v134
	v_pk_mul_f32 v[94:95], v[94:95], v[134:135] op_sel_hi:[1,0]
	v_pk_mul_f32 v[92:93], v[92:93], v[134:135] op_sel_hi:[1,0]
	v_pk_mul_f32 v[90:91], v[90:91], v[134:135] op_sel_hi:[1,0]
	v_pk_mul_f32 v[88:89], v[88:89], v[134:135] op_sel_hi:[1,0]
	v_pk_mul_f32 v[86:87], v[86:87], v[134:135] op_sel_hi:[1,0]
	v_pk_mul_f32 v[84:85], v[84:85], v[134:135] op_sel_hi:[1,0]
	v_pk_mul_f32 v[82:83], v[82:83], v[134:135] op_sel_hi:[1,0]
	v_pk_mul_f32 v[80:81], v[80:81], v[134:135] op_sel_hi:[1,0]
	v_pk_mul_f32 v[46:47], v[46:47], v[134:135] op_sel_hi:[1,0]
	v_pk_mul_f32 v[44:45], v[44:45], v[134:135] op_sel_hi:[1,0]
	v_pk_mul_f32 v[42:43], v[42:43], v[134:135] op_sel_hi:[1,0]
	v_pk_mul_f32 v[40:41], v[40:41], v[134:135] op_sel_hi:[1,0]
	v_pk_mul_f32 v[38:39], v[38:39], v[134:135] op_sel_hi:[1,0]
	v_pk_mul_f32 v[36:37], v[36:37], v[134:135] op_sel_hi:[1,0]
	v_pk_mul_f32 v[34:35], v[34:35], v[134:135] op_sel_hi:[1,0]
	v_pk_mul_f32 v[32:33], v[32:33], v[134:135] op_sel_hi:[1,0]
	s_branch .LBB0_1940
.LBB0_1941:
	s_mov_b64 s[24:25], 0
	s_branch .LBB0_1942
